# gemm_in K loop: fragment reads ordered by first use with counted lgkmcnt waits (MFMAs start after 2 reads)
# speedup vs baseline: 1.0148x; 1.0026x over previous
; DI void gemm_dma(f32x4 (&acc)[4][4], const bf16_t* Ap, int lda, const bf16_t* Bp, int ldb, int K, char* lds) {
;     ...
;   for (int kt = 0; kt < nk; ++kt) {
;     asm volatile("s_waitcnt vmcnt(0)" ::: "memory");
;     __builtin_amdgcn_s_barrier();
;     asm volatile("" ::: "memory");
;     if (kt + 1 < nk) issue(kt + 1);
;     const unsigned sa = lbase + (unsigned)((kt & 1) * 32768);
;     bf16x8 af[4], bfr[4], ag[4], bg[4];
;     asm volatile("ds_read_b128 %0, %8\n\tds_read_b128 %1, %8 offset:2048\n\tds_read_b128 %2, %8 offset:4096\n\tds_read_b128 %3, %8 offset:6144\n\t"
;                  "ds_read_b128 %4, %9\n\tds_read_b128 %5, %9 offset:2048\n\tds_read_b128 %6, %9 offset:4096\n\tds_read_b128 %7, %9 offset:6144"
;                  : "=&v"(af[0]), "=&v"(af[1]), "=&v"(af[2]), "=&v"(af[3]), "=&v"(bfr[0]), "=&v"(bfr[1]), "=&v"(bfr[2]), "=&v"(bfr[3])
;                  : "v"(sa + a0), "v"(sa + b0) : "memory");
;     asm volatile("ds_read_b128 %0, %16\n\tds_read_b128 %1, %16 offset:2048\n\tds_read_b128 %2, %16 offset:4096\n\tds_read_b128 %3, %16 offset:6144\n\t"
;                  "ds_read_b128 %4, %17\n\tds_read_b128 %5, %17 offset:2048\n\tds_read_b128 %6, %17 offset:4096\n\tds_read_b128 %7, %17 offset:6144\n\t"
;                  "s_waitcnt lgkmcnt(8)"
;                  : "=&v"(ag[0]), "=&v"(ag[1]), "=&v"(ag[2]), "=&v"(ag[3]), "=&v"(bg[0]), "=&v"(bg[1]), "=&v"(bg[2]), "=&v"(bg[3]),
;                    "+v"(af[0]), "+v"(af[1]), "+v"(af[2]), "+v"(af[3]), "+v"(bfr[0]), "+v"(bfr[1]), "+v"(bfr[2]), "+v"(bfr[3])
;                  : "v"(sa + a1), "v"(sa + b1) : "memory");
; #pragma unroll
;     for (int mi = 0; mi < 4; ++mi)
; #pragma unroll
;       for (int ni = 0; ni < 4; ++ni) acc[mi][ni] = __builtin_amdgcn_mfma_f32_16x16x32_bf16(bfr[ni], af[mi], acc[mi][ni], 0, 0, 0);
;     asm volatile("s_waitcnt lgkmcnt(0)" : "+v"(ag[0]), "+v"(ag[1]), "+v"(ag[2]), "+v"(ag[3]), "+v"(bg[0]), "+v"(bg[1]), "+v"(bg[2]), "+v"(bg[3]) :: "memory");
; #pragma unroll
;     for (int mi = 0; mi < 4; ++mi)
; #pragma unroll
;       for (int ni = 0; ni < 4; ++ni) acc[mi][ni] = __builtin_amdgcn_mfma_f32_16x16x32_bf16(bg[ni], ag[mi], acc[mi][ni], 0, 0, 0);
;   }
.LBB0_69:
	s_add_i32 s20, s3, 0x8000
	s_and_b32 s3, s3, 0x8000
	s_and_b32 s21, s20, 0x8000
	v_add_u32_e32 v0, s3, v86
	v_or_b32_e32 v122, s3, v89
	s_waitcnt vmcnt(0)
	v_add_u32_e32 v154, s3, v87
	v_add_u32_e32 v155, s3, v88
	s_add_i32 s3, s1, s21
	s_waitcnt vmcnt(0)
	s_barrier
	v_lshl_add_u64 v[90:91], v[66:67], 0, s[22:23]
	s_add_i32 s21, s3, 0x4000
	s_mov_b32 m0, s3
	v_lshl_add_u64 v[92:93], v[68:69], 0, s[22:23]
	global_load_lds_dwordx4 v[90:91], off
	s_mov_b32 m0, s21
	v_lshl_add_u64 v[94:95], v[74:75], 0, s[22:23]
	global_load_lds_dwordx4 v[92:93], off
	s_add_i32 m0, s3, 0x400
	v_lshl_add_u64 v[96:97], v[76:77], 0, s[22:23]
	global_load_lds_dwordx4 v[94:95], off
	s_add_i32 m0, s3, 0x4400
	v_lshl_add_u64 v[98:99], v[78:79], 0, s[22:23]
	global_load_lds_dwordx4 v[96:97], off
	s_add_i32 m0, s3, 0x800
	v_lshl_add_u64 v[100:101], v[80:81], 0, s[22:23]
	global_load_lds_dwordx4 v[98:99], off
	s_add_i32 m0, s3, 0x4800
	v_lshl_add_u64 v[102:103], v[82:83], 0, s[22:23]
	global_load_lds_dwordx4 v[100:101], off
	s_add_i32 m0, s3, 0xc00
	v_lshl_add_u64 v[104:105], v[84:85], 0, s[22:23]
	global_load_lds_dwordx4 v[102:103], off
	s_add_i32 m0, s3, 0x4c00
	s_add_u32 s22, s22, 0x80
	global_load_lds_dwordx4 v[104:105], off
	s_addc_u32 s23, s23, 0
	v_mov_b32_e32 v214, v122
	ds_read_b128 v[90:93], v0
	ds_read_b128 v[106:109], v214
	ds_read_b128 v[110:113], v214 offset:2048
	ds_read_b128 v[114:117], v214 offset:4096
	ds_read_b128 v[118:121], v214 offset:6144
	ds_read_b128 v[94:97], v0 offset:2048
	ds_read_b128 v[98:101], v0 offset:4096
	ds_read_b128 v[102:105], v0 offset:6144
	ds_read_b128 v[122:125], v154
	ds_read_b128 v[138:141], v155
	ds_read_b128 v[142:145], v155 offset:2048
	ds_read_b128 v[146:149], v155 offset:4096
	ds_read_b128 v[150:153], v155 offset:6144
	ds_read_b128 v[126:129], v154 offset:2048
	ds_read_b128 v[130:133], v154 offset:4096
	ds_read_b128 v[134:137], v154 offset:6144
	s_cmpk_lg_i32 s22, 0x780
	s_waitcnt lgkmcnt(14)
	v_mfma_f32_16x16x32_bf16 v[62:65], v[106:109], v[90:93], v[62:65]
	s_waitcnt lgkmcnt(13)
	v_mfma_f32_16x16x32_bf16 v[58:61], v[110:113], v[90:93], v[58:61]
	s_waitcnt lgkmcnt(12)
	v_mfma_f32_16x16x32_bf16 v[54:57], v[114:117], v[90:93], v[54:57]
	s_waitcnt lgkmcnt(11)
	v_mfma_f32_16x16x32_bf16 v[46:49], v[118:121], v[90:93], v[46:49]
	s_waitcnt lgkmcnt(10)
	v_mfma_f32_16x16x32_bf16 v[42:45], v[106:109], v[94:97], v[42:45]
	v_mfma_f32_16x16x32_bf16 v[38:41], v[110:113], v[94:97], v[38:41]
	v_mfma_f32_16x16x32_bf16 v[34:37], v[114:117], v[94:97], v[34:37]
	v_mfma_f32_16x16x32_bf16 v[30:33], v[118:121], v[94:97], v[30:33]
	s_waitcnt lgkmcnt(9)
	v_mfma_f32_16x16x32_bf16 v[26:29], v[106:109], v[98:101], v[26:29]
	v_mfma_f32_16x16x32_bf16 v[22:25], v[110:113], v[98:101], v[22:25]
	v_mfma_f32_16x16x32_bf16 v[18:21], v[114:117], v[98:101], v[18:21]
	v_mfma_f32_16x16x32_bf16 v[14:17], v[118:121], v[98:101], v[14:17]
	s_waitcnt lgkmcnt(8)
	v_mfma_f32_16x16x32_bf16 v[10:13], v[106:109], v[102:105], v[10:13]
	v_mfma_f32_16x16x32_bf16 v[6:9], v[110:113], v[102:105], v[6:9]
	v_mfma_f32_16x16x32_bf16 v[2:5], v[114:117], v[102:105], v[2:5]
	v_mfma_f32_16x16x32_bf16 v[50:53], v[118:121], v[102:105], v[50:53]
	s_waitcnt lgkmcnt(6)
	v_mfma_f32_16x16x32_bf16 v[62:65], v[138:141], v[122:125], v[62:65]
	s_waitcnt lgkmcnt(5)
	v_mfma_f32_16x16x32_bf16 v[58:61], v[142:145], v[122:125], v[58:61]
	s_waitcnt lgkmcnt(4)
	v_mfma_f32_16x16x32_bf16 v[54:57], v[146:149], v[122:125], v[54:57]
	s_waitcnt lgkmcnt(3)
	v_mfma_f32_16x16x32_bf16 v[46:49], v[150:153], v[122:125], v[46:49]
	s_waitcnt lgkmcnt(2)
	v_mfma_f32_16x16x32_bf16 v[42:45], v[138:141], v[126:129], v[42:45]
	v_mfma_f32_16x16x32_bf16 v[38:41], v[142:145], v[126:129], v[38:41]
	v_mfma_f32_16x16x32_bf16 v[34:37], v[146:149], v[126:129], v[34:37]
	v_mfma_f32_16x16x32_bf16 v[30:33], v[150:153], v[126:129], v[30:33]
	s_waitcnt lgkmcnt(1)
	v_mfma_f32_16x16x32_bf16 v[26:29], v[138:141], v[130:133], v[26:29]
	v_mfma_f32_16x16x32_bf16 v[22:25], v[142:145], v[130:133], v[22:25]
	v_mfma_f32_16x16x32_bf16 v[18:21], v[146:149], v[130:133], v[18:21]
	v_mfma_f32_16x16x32_bf16 v[14:17], v[150:153], v[130:133], v[14:17]
	s_waitcnt lgkmcnt(0)
	v_mfma_f32_16x16x32_bf16 v[10:13], v[138:141], v[134:137], v[10:13]
	v_mfma_f32_16x16x32_bf16 v[6:9], v[142:145], v[134:137], v[6:9]
	v_mfma_f32_16x16x32_bf16 v[2:5], v[146:149], v[134:137], v[2:5]
	v_mfma_f32_16x16x32_bf16 v[50:53], v[150:153], v[134:137], v[50:53]
	s_mov_b32 s3, s20
	s_cbranch_scc1 .LBB0_69
; DI void gemm_dma(f32x4 (&acc)[4][4], const bf16_t* Ap, int lda, const bf16_t* Bp, int ldb, int K, char* lds) {
;     ...
; #pragma unroll
;     for (int mi = 0; mi < 4; ++mi)
; #pragma unroll
;       for (int ni = 0; ni < 4; ++ni) acc[mi][ni] = __builtin_amdgcn_mfma_f32_16x16x32_bf16(bfr[ni], af[mi], acc[mi][ni], 0, 0, 0);
;     asm volatile("s_waitcnt lgkmcnt(0)" : "+v"(ag[0]), "+v"(ag[1]), "+v"(ag[2]), "+v"(ag[3]), "+v"(bg[0]), "+v"(bg[1]), "+v"(bg[2]), "+v"(bg[3]) :: "memory");
; #pragma unroll
;     for (int mi = 0; mi < 4; ++mi)
; #pragma unroll
;       for (int ni = 0; ni < 4; ++ni) acc[mi][ni] = __builtin_amdgcn_mfma_f32_16x16x32_bf16(bg[ni], ag[mi], acc[mi][ni], 0, 0, 0);
;   }
; DI void phase_gemm_in(const Params& p, int l, char* lds) {
;     ...
;         const float rs = rsqrtf(p.ss1[mt * 128 + wm * 64 + mi * 16 + l15] * (1.0f / 1024.0f) + 1e-6f);
; #pragma unroll
;         for (int ni = 0; ni < 4; ++ni) acc[mi][ni] = acc[mi][ni] * rs;
;       }
;     }
;     int kind;
;     if (nt < 13) kind = 0; else if (nt < 17) kind = 1; else if (nt < 21) kind = 2; else if (nt < 25) kind = 3; else if (nt < 29) kind = 4; else if (nt < 33) kind = 1; else kind = 5;
	s_waitcnt vmcnt(0)
	s_barrier
	v_add_u32_e32 v0, 0x8000, v86
	v_or_b32_e32 v86, 0x8000, v89
	ds_read_b128 v[66:69], v0
	ds_read_b128 v[74:77], v0 offset:2048
	ds_read_b128 v[78:81], v0 offset:4096
	ds_read_b128 v[82:85], v0 offset:6144
	ds_read_b128 v[90:93], v86
	ds_read_b128 v[94:97], v86 offset:2048
	ds_read_b128 v[98:101], v86 offset:4096
	ds_read_b128 v[102:105], v86 offset:6144
	v_add_u32_e32 v0, 0x8000, v87
	v_add_u32_e32 v134, 0x8000, v88
	ds_read_b128 v[86:89], v0
	ds_read_b128 v[106:109], v0 offset:2048
	ds_read_b128 v[110:113], v0 offset:4096
	ds_read_b128 v[114:117], v0 offset:6144
	ds_read_b128 v[118:121], v134
	ds_read_b128 v[122:125], v134 offset:2048
	ds_read_b128 v[126:129], v134 offset:4096
	ds_read_b128 v[130:133], v134 offset:6144
	s_waitcnt lgkmcnt(8)
	s_lshl_b32 s46, s2, 7
	v_mfma_f32_16x16x32_bf16 v[62:65], v[90:93], v[66:69], v[62:65]
	s_waitcnt lgkmcnt(0)
	v_readlane_b32 s20, v254, 52
	v_readlane_b32 s21, v254, 53
	v_mfma_f32_16x16x32_bf16 v[46:49], v[102:105], v[66:69], v[46:49]
	s_barrier
	v_mfma_f32_16x16x32_bf16 v[42:45], v[90:93], v[74:77], v[42:45]
	v_readlane_b32 s22, v254, 54
	v_readlane_b32 s23, v254, 55
	v_readlane_b32 s24, v254, 56
	v_mfma_f32_16x16x32_bf16 v[38:41], v[94:97], v[74:77], v[38:41]
	v_readlane_b32 s25, v254, 57
	v_readlane_b32 s26, v254, 58
	v_readlane_b32 s27, v254, 59
	v_mfma_f32_16x16x32_bf16 v[34:37], v[98:101], v[74:77], v[34:37]
	s_cmp_gt_i32 s0, 12
	s_mov_b64 s[2:3], 0
	s_cselect_b64 s[30:31], -1, 0
	v_mfma_f32_16x16x32_bf16 v[30:33], v[102:105], v[74:77], v[30:33]
	s_cmp_lt_i32 s0, 13
	s_mov_b64 s[26:27], 0
	s_mov_b64 s[24:25], 0
	v_mfma_f32_16x16x32_bf16 v[26:29], v[90:93], v[78:81], v[26:29]
	s_mov_b64 s[22:23], 0
	v_mfma_f32_16x16x32_bf16 v[18:21], v[98:101], v[78:81], v[18:21]
	v_mfma_f32_16x16x32_bf16 v[14:17], v[102:105], v[78:81], v[14:17]
	v_mfma_f32_16x16x32_bf16 v[134:137], v[98:101], v[66:69], v[54:57]
	v_mfma_f32_16x16x32_bf16 v[54:57], v[118:121], v[86:89], v[62:65]
	v_mfma_f32_16x16x32_bf16 v[62:65], v[130:133], v[86:89], v[46:49]
	v_mfma_f32_16x16x32_bf16 v[46:49], v[118:121], v[106:109], v[42:45]
	v_mfma_f32_16x16x32_bf16 v[42:45], v[122:125], v[106:109], v[38:41]
	v_mfma_f32_16x16x32_bf16 v[38:41], v[126:129], v[106:109], v[34:37]
	v_mfma_f32_16x16x32_bf16 v[34:37], v[130:133], v[106:109], v[30:33]
	v_mfma_f32_16x16x32_bf16 v[30:33], v[118:121], v[110:113], v[26:29]
	v_mfma_f32_16x16x32_bf16 v[26:29], v[126:129], v[110:113], v[18:21]
	v_mfma_f32_16x16x32_bf16 v[18:21], v[130:133], v[110:113], v[14:17]
	s_nop 2
	v_add_u32_e32 v14, s46, v71
	v_ashrrev_i32_e32 v15, 31, v14
	v_lshl_add_u64 v[74:75], v[14:15], 2, s[20:21]
	v_mfma_f32_16x16x32_bf16 v[58:61], v[94:97], v[66:69], v[58:61]
	v_mfma_f32_16x16x32_bf16 v[66:69], v[102:105], v[82:85], v[50:53]
	global_load_dword v0, v[74:75], off
	global_load_dword v105, v[74:75], off offset:64
	global_load_dword v104, v[74:75], off offset:128
	global_load_dword v102, v[74:75], off offset:192
	v_mfma_f32_16x16x32_bf16 v[22:25], v[94:97], v[78:81], v[22:25]
	v_mfma_f32_16x16x32_bf16 v[10:13], v[90:93], v[82:85], v[10:13]
	v_mfma_f32_16x16x32_bf16 v[6:9], v[94:97], v[82:85], v[6:9]
	v_mfma_f32_16x16x32_bf16 v[2:5], v[98:101], v[82:85], v[2:5]
	v_mfma_f32_16x16x32_bf16 v[50:53], v[122:125], v[86:89], v[58:61]
	v_mfma_f32_16x16x32_bf16 v[58:61], v[126:129], v[86:89], v[134:137]
	v_mfma_f32_16x16x32_bf16 v[22:25], v[122:125], v[110:113], v[22:25]
	v_mfma_f32_16x16x32_bf16 v[14:17], v[118:121], v[114:117], v[10:13]
	v_mfma_f32_16x16x32_bf16 v[10:13], v[122:125], v[114:117], v[6:9]
	v_mfma_f32_16x16x32_bf16 v[6:9], v[126:129], v[114:117], v[2:5]
	v_mfma_f32_16x16x32_bf16 v[2:5], v[130:133], v[114:117], v[66:69]
	s_cbranch_scc1 .LBB0_77
	s_cmp_lt_u32 s0, 17
	s_cbranch_scc1 .LBB0_75
	s_cmp_lt_u32 s0, 21
	s_cbranch_scc1 .LBB0_76
	s_mov_b64 s[22:23], -1
	s_cmp_lt_u32 s0, 25
	s_cbranch_scc1 .LBB0_77
	s_sub_i32 s1, s0, 29
	s_cmp_lt_u32 s1, 4
	s_cselect_b64 s[2:3], -1, 0
	s_cmp_gt_u32 s0, 32
	s_mov_b64 s[22:23], 0
	s_cselect_b64 s[26:27], -1, 0
	s_branch .LBB0_77
